# up K-loop: trailing wave half (wr=1) runs a copy of the loop whose LDS fragment reads for the next segment are issued inside its own MFMA segment (software pipelining of ds_reads; load segments hold o
# baseline (speedup 1.0000x reference)
; #define PG8_STAGE(bufoff, gbase, voff) do { _Pragma("unroll") for (int _i = 0; _i < 2; ++_i) \
;         __builtin_amdgcn_global_load_lds((const unsigned*)((const char*)(gbase) + (voff)[_i]), (PG8_LAS unsigned*)(lds + (bufoff) + ldsw + _i * 8192), 16, 0, 0); } while (0)
; #define PG8_LDA(dst, b, h) do { _Pragma("unroll") for (int m = 0; m < 4; ++m) _Pragma("unroll") for (int k = 0; k < 2; ++k) dst[m][k] = *(const PG8_LAS bf16x8*)(lds + PG8_SA(b, h) + aoff + m * 2048 + k * 1024); } while (0)
; #define PG8_LDB(dst, b, h) do { _Pragma("unroll") for (int n = 0; n < 2; ++n) _Pragma("unroll") for (int k = 0; k < 2; ++k) dst[n][k] = *(const PG8_LAS bf16x8*)(lds + PG8_SB(b, h) + boff + n * 2048 + k * 1024); } while (0)
; #define PG8_MMA(ai, bj, At, Bt) do { __builtin_amdgcn_s_setprio(1); _Pragma("unroll") for (int m = 0; m < 4; ++m) _Pragma("unroll") for (int n = 0; n < 2; ++n) _Pragma("unroll") for (int k = 0; k < 2; ++k) \
;         acc[ai][bj][m][n] = __builtin_amdgcn_mfma_f32_16x16x32_bf16(Bt[n][k], At[m][k], acc[ai][bj][m][n], 0, 0, 0); __builtin_amdgcn_s_setprio(0); } while (0)
; #define PG8_WAIT_V(n) asm volatile("s_waitcnt vmcnt(" #n ")" ::: "memory")
; #define PG8_WAIT_L(n) asm volatile("s_waitcnt lgkmcnt(" #n ")" ::: "memory")
; #define PG8_BAR __builtin_amdgcn_s_barrier()
; #define PG8_SCHED __builtin_amdgcn_sched_barrier(0)
; template <class Epi, class Sched, bool ALIGN_EPI = false, bool SP2 = false>
; __device__ __forceinline__ void gemm_phase(PG8_LAS unsigned char* lds, const Gemm g, const Sched& S, const Epi& E) {
;     ...
;             if constexpr (SP2) {
;             PG8_LDB(B0, 0, 0); PG8_LDB(B1, 0, 1); PG8_SCHED; PG8_LDA(At, 0, 0); PG8_STAGE(PG8_SA(1, 1), a1 + hstep, voffA);
;             PG8_WAIT_V(8); PG8_WAIT_L(0); PG8_BAR; PG8_MMA(0, 0, At, B0); PG8_MMA(0, 1, At, B1); PG8_BAR; PG8_SCHED;
;             PG8_LDA(At, 0, 1); PG8_STAGE(PG8_SB(0, 0), b2, voffB); PG8_STAGE(PG8_SB(0, 1), b2 + hstep, voffB); PG8_STAGE(PG8_SA(0, 0), a2, voffA);
;             PG8_WAIT_V(8); PG8_WAIT_L(0); PG8_BAR; PG8_MMA(1, 0, At, B0); PG8_MMA(1, 1, At, B1); PG8_BAR; PG8_SCHED;
;             PG8_LDB(B0, 1, 0); PG8_LDB(B1, 1, 1); PG8_SCHED; PG8_LDA(At, 1, 0); PG8_STAGE(PG8_SA(0, 1), a2 + hstep, voffA);
;             PG8_WAIT_V(8); PG8_WAIT_L(0); PG8_BAR; PG8_MMA(0, 0, At, B0); PG8_MMA(0, 1, At, B1); PG8_BAR; PG8_SCHED;
.Lup_peel_w1:
	ds_read_b128 v[140:143], v254
	ds_read_b128 v[168:171], v254 offset:1024
	ds_read_b128 v[172:175], v254 offset:2048
	ds_read_b128 v[176:179], v254 offset:3072
	ds_read_b128 v[180:183], v254 offset:16384
	ds_read_b128 v[184:187], v254 offset:17408
	ds_read_b128 v[188:191], v254 offset:18432
	ds_read_b128 v[210:213], v254 offset:19456
	s_add_u32 s16, s14, 0xfffc0080
	s_addc_u32 s17, s15, -1
	s_cmp_eq_u32 s53, 12
	s_cselect_b32 s19, s7, s17
	s_cselect_b32 s18, s49, s16
	s_cselect_b32 s17, s5, s52
	s_cselect_b32 s16, s50, s51
	s_mov_b32 m0, s43
	ds_read_b128 v[214:217], v165
	ds_read_b128 v[218:221], v165 offset:1024
	ds_read_b128 v[222:225], v165 offset:2048
	ds_read_b128 v[226:229], v165 offset:3072
	ds_read_b128 v[230:233], v165 offset:4096
	ds_read_b128 v[234:237], v165 offset:5120
	ds_read_b128 v[238:241], v165 offset:6144
	ds_read_b128 v[242:245], v165 offset:7168
	global_load_lds_dwordx4 v136, s[14:15]
	s_mov_b32 m0, s44
	s_nop 0
	global_load_lds_dwordx4 v138, s[14:15]
	s_waitcnt vmcnt(8)
	s_waitcnt lgkmcnt(0)
	s_barrier
	s_setprio 1
	v_mfma_f32_16x16x32_bf16 v[124:127], v[140:143], v[214:217], 0
	v_mfma_f32_16x16x32_bf16 v[116:119], v[172:175], v[214:217], 0
	v_mfma_f32_16x16x32_bf16 v[108:111], v[140:143], v[222:225], 0
	v_mfma_f32_16x16x32_bf16 v[100:103], v[172:175], v[222:225], 0
	v_mfma_f32_16x16x32_bf16 v[92:95], v[140:143], v[230:233], 0
	v_mfma_f32_16x16x32_bf16 v[84:87], v[172:175], v[230:233], 0
	v_mfma_f32_16x16x32_bf16 v[76:79], v[140:143], v[238:241], 0
	v_mfma_f32_16x16x32_bf16 v[68:71], v[172:175], v[238:241], 0
	v_mfma_f32_16x16x32_bf16 v[124:127], v[168:171], v[218:221], v[124:127]
	v_mfma_f32_16x16x32_bf16 v[116:119], v[176:179], v[218:221], v[116:119]
	v_mfma_f32_16x16x32_bf16 v[108:111], v[168:171], v[226:229], v[108:111]
	v_mfma_f32_16x16x32_bf16 v[100:103], v[176:179], v[226:229], v[100:103]
	v_mfma_f32_16x16x32_bf16 v[92:95], v[168:171], v[234:237], v[92:95]
	v_mfma_f32_16x16x32_bf16 v[84:87], v[176:179], v[234:237], v[84:87]
	v_mfma_f32_16x16x32_bf16 v[76:79], v[168:171], v[242:245], v[76:79]
	v_mfma_f32_16x16x32_bf16 v[68:71], v[176:179], v[242:245], v[68:71]
	v_mfma_f32_16x16x32_bf16 v[120:123], v[180:183], v[214:217], 0
	v_mfma_f32_16x16x32_bf16 v[112:115], v[188:191], v[214:217], 0
	ds_read_b128 v[214:217], v165 offset:16384
	v_mfma_f32_16x16x32_bf16 v[104:107], v[180:183], v[222:225], 0
	v_mfma_f32_16x16x32_bf16 v[96:99], v[188:191], v[222:225], 0
	ds_read_b128 v[222:225], v165 offset:18432
	v_mfma_f32_16x16x32_bf16 v[88:91], v[180:183], v[230:233], 0
	v_mfma_f32_16x16x32_bf16 v[80:83], v[188:191], v[230:233], 0
	ds_read_b128 v[230:233], v165 offset:20480
	v_mfma_f32_16x16x32_bf16 v[72:75], v[180:183], v[238:241], 0
	v_mfma_f32_16x16x32_bf16 v[64:67], v[188:191], v[238:241], 0
	ds_read_b128 v[238:241], v165 offset:22528
	v_mfma_f32_16x16x32_bf16 v[120:123], v[184:187], v[218:221], v[120:123]
	v_mfma_f32_16x16x32_bf16 v[112:115], v[210:213], v[218:221], v[112:115]
	ds_read_b128 v[218:221], v165 offset:17408
	v_mfma_f32_16x16x32_bf16 v[104:107], v[184:187], v[226:229], v[104:107]
	v_mfma_f32_16x16x32_bf16 v[96:99], v[210:213], v[226:229], v[96:99]
	ds_read_b128 v[226:229], v165 offset:19456
	v_mfma_f32_16x16x32_bf16 v[88:91], v[184:187], v[234:237], v[88:91]
	v_mfma_f32_16x16x32_bf16 v[80:83], v[210:213], v[234:237], v[80:83]
	ds_read_b128 v[234:237], v165 offset:21504
	v_mfma_f32_16x16x32_bf16 v[72:75], v[184:187], v[242:245], v[72:75]
	v_mfma_f32_16x16x32_bf16 v[64:67], v[210:213], v[242:245], v[64:67]
	ds_read_b128 v[242:245], v165 offset:23552
	s_setprio 0
	s_barrier
	s_mov_b32 m0, s27
	s_add_u32 s54, s16, 0x40000
	s_addc_u32 s55, s17, 0
	global_load_lds_dwordx4 v132, s[16:17]
	s_mov_b32 m0, s28
	s_nop 0
	global_load_lds_dwordx4 v128, s[16:17]
	s_mov_b32 m0, s29
	s_nop 0
	global_load_lds_dwordx4 v132, s[54:55]
	s_mov_b32 m0, s30
	s_nop 0
	global_load_lds_dwordx4 v128, s[54:55]
	s_mov_b32 m0, s22
	s_nop 0
	global_load_lds_dwordx4 v134, s[18:19]
	s_mov_b32 m0, s31
	s_nop 0
	global_load_lds_dwordx4 v130, s[18:19]
	s_waitcnt vmcnt(8)
	s_waitcnt lgkmcnt(0)
	s_barrier
	s_setprio 1
	v_mfma_f32_16x16x32_bf16 v[60:63], v[140:143], v[214:217], 0
	v_mfma_f32_16x16x32_bf16 v[52:55], v[172:175], v[214:217], 0
	v_mfma_f32_16x16x32_bf16 v[44:47], v[140:143], v[222:225], 0
	v_mfma_f32_16x16x32_bf16 v[36:39], v[172:175], v[222:225], 0
	v_mfma_f32_16x16x32_bf16 v[28:31], v[140:143], v[230:233], 0
	v_mfma_f32_16x16x32_bf16 v[20:23], v[172:175], v[230:233], 0
	v_mfma_f32_16x16x32_bf16 v[12:15], v[140:143], v[238:241], 0
	ds_read_b128 v[140:143], v254 offset:32768
	v_mfma_f32_16x16x32_bf16 v[4:7], v[172:175], v[238:241], 0
	ds_read_b128 v[172:175], v254 offset:34816
	v_mfma_f32_16x16x32_bf16 v[60:63], v[168:171], v[218:221], v[60:63]
	v_mfma_f32_16x16x32_bf16 v[52:55], v[176:179], v[218:221], v[52:55]
	v_mfma_f32_16x16x32_bf16 v[44:47], v[168:171], v[226:229], v[44:47]
	v_mfma_f32_16x16x32_bf16 v[36:39], v[176:179], v[226:229], v[36:39]
	v_mfma_f32_16x16x32_bf16 v[28:31], v[168:171], v[234:237], v[28:31]
	v_mfma_f32_16x16x32_bf16 v[20:23], v[176:179], v[234:237], v[20:23]
	v_mfma_f32_16x16x32_bf16 v[12:15], v[168:171], v[242:245], v[12:15]
	ds_read_b128 v[168:171], v254 offset:33792
	v_mfma_f32_16x16x32_bf16 v[4:7], v[176:179], v[242:245], v[4:7]
	ds_read_b128 v[176:179], v254 offset:35840
	v_mfma_f32_16x16x32_bf16 v[56:59], v[180:183], v[214:217], 0
	v_mfma_f32_16x16x32_bf16 v[48:51], v[188:191], v[214:217], 0
	ds_read_b128 v[214:217], v165 offset:32768
	v_mfma_f32_16x16x32_bf16 v[40:43], v[180:183], v[222:225], 0
	v_mfma_f32_16x16x32_bf16 v[32:35], v[188:191], v[222:225], 0
	ds_read_b128 v[222:225], v165 offset:34816
	v_mfma_f32_16x16x32_bf16 v[24:27], v[180:183], v[230:233], 0
	v_mfma_f32_16x16x32_bf16 v[16:19], v[188:191], v[230:233], 0
	ds_read_b128 v[230:233], v165 offset:36864
	v_mfma_f32_16x16x32_bf16 v[8:11], v[180:183], v[238:241], 0
	ds_read_b128 v[180:183], v254 offset:49152
	v_mfma_f32_16x16x32_bf16 v[0:3], v[188:191], v[238:241], 0
	ds_read_b128 v[188:191], v254 offset:51200
	ds_read_b128 v[238:241], v165 offset:38912
	v_mfma_f32_16x16x32_bf16 v[56:59], v[184:187], v[218:221], v[56:59]
	v_mfma_f32_16x16x32_bf16 v[48:51], v[210:213], v[218:221], v[48:51]
	ds_read_b128 v[218:221], v165 offset:33792
	v_mfma_f32_16x16x32_bf16 v[40:43], v[184:187], v[226:229], v[40:43]
	v_mfma_f32_16x16x32_bf16 v[32:35], v[210:213], v[226:229], v[32:35]
	ds_read_b128 v[226:229], v165 offset:35840
	v_mfma_f32_16x16x32_bf16 v[24:27], v[184:187], v[234:237], v[24:27]
	v_mfma_f32_16x16x32_bf16 v[16:19], v[210:213], v[234:237], v[16:19]
	ds_read_b128 v[234:237], v165 offset:37888
	v_mfma_f32_16x16x32_bf16 v[8:11], v[184:187], v[242:245], v[8:11]
	ds_read_b128 v[184:187], v254 offset:50176
	v_mfma_f32_16x16x32_bf16 v[0:3], v[210:213], v[242:245], v[0:3]
	ds_read_b128 v[210:213], v254 offset:52224
	ds_read_b128 v[242:245], v165 offset:39936
	s_setprio 0
	s_barrier
; #define PG8_STAGE(bufoff, gbase, voff) do { _Pragma("unroll") for (int _i = 0; _i < 2; ++_i) \
;         __builtin_amdgcn_global_load_lds((const unsigned*)((const char*)(gbase) + (voff)[_i]), (PG8_LAS unsigned*)(lds + (bufoff) + ldsw + _i * 8192), 16, 0, 0); } while (0)
; #define PG8_LDA(dst, b, h) do { _Pragma("unroll") for (int m = 0; m < 4; ++m) _Pragma("unroll") for (int k = 0; k < 2; ++k) dst[m][k] = *(const PG8_LAS bf16x8*)(lds + PG8_SA(b, h) + aoff + m * 2048 + k * 1024); } while (0)
; #define PG8_LDB(dst, b, h) do { _Pragma("unroll") for (int n = 0; n < 2; ++n) _Pragma("unroll") for (int k = 0; k < 2; ++k) dst[n][k] = *(const PG8_LAS bf16x8*)(lds + PG8_SB(b, h) + boff + n * 2048 + k * 1024); } while (0)
; #define PG8_MMA(ai, bj, At, Bt) do { __builtin_amdgcn_s_setprio(1); _Pragma("unroll") for (int m = 0; m < 4; ++m) _Pragma("unroll") for (int n = 0; n < 2; ++n) _Pragma("unroll") for (int k = 0; k < 2; ++k) \
;         acc[ai][bj][m][n] = __builtin_amdgcn_mfma_f32_16x16x32_bf16(Bt[n][k], At[m][k], acc[ai][bj][m][n], 0, 0, 0); __builtin_amdgcn_s_setprio(0); } while (0)
; #define PG8_WAIT_V(n) asm volatile("s_waitcnt vmcnt(" #n ")" ::: "memory")
; #define PG8_WAIT_L(n) asm volatile("s_waitcnt lgkmcnt(" #n ")" ::: "memory")
; #define PG8_BAR __builtin_amdgcn_s_barrier()
; #define PG8_SCHED __builtin_amdgcn_sched_barrier(0)
; template <class Epi, class Sched, bool ALIGN_EPI = false, bool SP2 = false>
; __device__ __forceinline__ void gemm_phase(PG8_LAS unsigned char* lds, const Gemm g, const Sched& S, const Epi& E) {
;     ...
;             PG8_LDB(B0, 1, 0); PG8_LDB(B1, 1, 1); PG8_SCHED; PG8_LDA(At, 1, 0); PG8_STAGE(PG8_SA(0, 1), a2 + hstep, voffA);
;             PG8_WAIT_V(8); PG8_WAIT_L(0); PG8_BAR; PG8_MMA(0, 0, At, B0); PG8_MMA(0, 1, At, B1); PG8_BAR; PG8_SCHED;
;             PG8_LDA(At, 1, 1); PG8_STAGE(PG8_SB(1, 0), b3, voffB); PG8_STAGE(PG8_SB(1, 1), b3 + hstep, voffB); PG8_STAGE(PG8_SA(1, 0), a3, voffA);
;             PG8_WAIT_V(8); PG8_WAIT_L(0); PG8_BAR; PG8_MMA(1, 0, At, B0); PG8_MMA(1, 1, At, B1); PG8_BAR; PG8_SCHED;
	s_add_u32 s18, s18, 0x40000
	s_addc_u32 s19, s19, 0
	s_mov_b32 m0, s33
	global_load_lds_dwordx4 v134, s[18:19]
	s_mov_b32 m0, s34
	s_nop 0
	global_load_lds_dwordx4 v130, s[18:19]
	s_waitcnt vmcnt(8)
	s_waitcnt lgkmcnt(0)
	s_barrier
	s_setprio 1
	v_mfma_f32_16x16x32_bf16 v[124:127], v[140:143], v[214:217], v[124:127]
	v_mfma_f32_16x16x32_bf16 v[116:119], v[172:175], v[214:217], v[116:119]
	v_mfma_f32_16x16x32_bf16 v[108:111], v[140:143], v[222:225], v[108:111]
	v_mfma_f32_16x16x32_bf16 v[100:103], v[172:175], v[222:225], v[100:103]
	v_mfma_f32_16x16x32_bf16 v[92:95], v[140:143], v[230:233], v[92:95]
	v_mfma_f32_16x16x32_bf16 v[84:87], v[172:175], v[230:233], v[84:87]
	v_mfma_f32_16x16x32_bf16 v[76:79], v[140:143], v[238:241], v[76:79]
	v_mfma_f32_16x16x32_bf16 v[68:71], v[172:175], v[238:241], v[68:71]
	v_mfma_f32_16x16x32_bf16 v[124:127], v[168:171], v[218:221], v[124:127]
	v_mfma_f32_16x16x32_bf16 v[116:119], v[176:179], v[218:221], v[116:119]
	v_mfma_f32_16x16x32_bf16 v[108:111], v[168:171], v[226:229], v[108:111]
	v_mfma_f32_16x16x32_bf16 v[100:103], v[176:179], v[226:229], v[100:103]
	v_mfma_f32_16x16x32_bf16 v[92:95], v[168:171], v[234:237], v[92:95]
	v_mfma_f32_16x16x32_bf16 v[84:87], v[176:179], v[234:237], v[84:87]
	v_mfma_f32_16x16x32_bf16 v[76:79], v[168:171], v[242:245], v[76:79]
	v_mfma_f32_16x16x32_bf16 v[68:71], v[176:179], v[242:245], v[68:71]
	v_mfma_f32_16x16x32_bf16 v[120:123], v[180:183], v[214:217], v[120:123]
	v_mfma_f32_16x16x32_bf16 v[112:115], v[188:191], v[214:217], v[112:115]
	ds_read_b128 v[214:217], v165 offset:49152
	v_mfma_f32_16x16x32_bf16 v[104:107], v[180:183], v[222:225], v[104:107]
	v_mfma_f32_16x16x32_bf16 v[96:99], v[188:191], v[222:225], v[96:99]
	ds_read_b128 v[222:225], v165 offset:51200
	v_mfma_f32_16x16x32_bf16 v[88:91], v[180:183], v[230:233], v[88:91]
	v_mfma_f32_16x16x32_bf16 v[80:83], v[188:191], v[230:233], v[80:83]
	ds_read_b128 v[230:233], v165 offset:53248
	v_mfma_f32_16x16x32_bf16 v[72:75], v[180:183], v[238:241], v[72:75]
	v_mfma_f32_16x16x32_bf16 v[64:67], v[188:191], v[238:241], v[64:67]
	ds_read_b128 v[238:241], v165 offset:55296
	v_mfma_f32_16x16x32_bf16 v[120:123], v[184:187], v[218:221], v[120:123]
	v_mfma_f32_16x16x32_bf16 v[112:115], v[210:213], v[218:221], v[112:115]
	ds_read_b128 v[218:221], v165 offset:50176
	v_mfma_f32_16x16x32_bf16 v[104:107], v[184:187], v[226:229], v[104:107]
	v_mfma_f32_16x16x32_bf16 v[96:99], v[210:213], v[226:229], v[96:99]
	ds_read_b128 v[226:229], v165 offset:52224
	v_mfma_f32_16x16x32_bf16 v[88:91], v[184:187], v[234:237], v[88:91]
	v_mfma_f32_16x16x32_bf16 v[80:83], v[210:213], v[234:237], v[80:83]
	ds_read_b128 v[234:237], v165 offset:54272
	v_mfma_f32_16x16x32_bf16 v[72:75], v[184:187], v[242:245], v[72:75]
	v_mfma_f32_16x16x32_bf16 v[64:67], v[210:213], v[242:245], v[64:67]
	ds_read_b128 v[242:245], v165 offset:56320
	s_setprio 0
	s_barrier
	s_mov_b32 m0, s37
	s_add_u32 s16, s16, 0x40080
	s_addc_u32 s17, s17, 0
	s_add_u32 s98, s16, 0xfffc0000
	s_addc_u32 s99, s17, -1
	global_load_lds_dwordx4 v132, s[98:99]
	s_mov_b32 m0, s38
	s_nop 0
	global_load_lds_dwordx4 v128, s[98:99]
	s_mov_b32 m0, s41
	s_nop 0
	global_load_lds_dwordx4 v132, s[16:17]
	s_mov_b32 m0, s42
	s_nop 0
	global_load_lds_dwordx4 v128, s[16:17]
	s_mov_b32 m0, s39
	s_nop 0
	s_add_u32 s100, s18, 0xfffc0080
	s_addc_u32 s101, s19, -1
	global_load_lds_dwordx4 v134, s[100:101]
	s_mov_b32 m0, s40
	s_nop 0
	global_load_lds_dwordx4 v130, s[100:101]
	s_waitcnt vmcnt(8)
	s_waitcnt lgkmcnt(0)
	s_barrier
	s_setprio 1
	v_mfma_f32_16x16x32_bf16 v[60:63], v[140:143], v[214:217], v[60:63]
	v_mfma_f32_16x16x32_bf16 v[52:55], v[172:175], v[214:217], v[52:55]
	v_mfma_f32_16x16x32_bf16 v[44:47], v[140:143], v[222:225], v[44:47]
	v_mfma_f32_16x16x32_bf16 v[36:39], v[172:175], v[222:225], v[36:39]
	v_mfma_f32_16x16x32_bf16 v[28:31], v[140:143], v[230:233], v[28:31]
	v_mfma_f32_16x16x32_bf16 v[20:23], v[172:175], v[230:233], v[20:23]
	v_mfma_f32_16x16x32_bf16 v[12:15], v[140:143], v[238:241], v[12:15]
	ds_read_b128 v[140:143], v254
	v_mfma_f32_16x16x32_bf16 v[4:7], v[172:175], v[238:241], v[4:7]
	ds_read_b128 v[172:175], v254 offset:2048
	v_mfma_f32_16x16x32_bf16 v[60:63], v[168:171], v[218:221], v[60:63]
	v_mfma_f32_16x16x32_bf16 v[52:55], v[176:179], v[218:221], v[52:55]
	v_mfma_f32_16x16x32_bf16 v[44:47], v[168:171], v[226:229], v[44:47]
	v_mfma_f32_16x16x32_bf16 v[36:39], v[176:179], v[226:229], v[36:39]
	v_mfma_f32_16x16x32_bf16 v[28:31], v[168:171], v[234:237], v[28:31]
	v_mfma_f32_16x16x32_bf16 v[20:23], v[176:179], v[234:237], v[20:23]
	v_mfma_f32_16x16x32_bf16 v[12:15], v[168:171], v[242:245], v[12:15]
	ds_read_b128 v[168:171], v254 offset:1024
	v_mfma_f32_16x16x32_bf16 v[4:7], v[176:179], v[242:245], v[4:7]
	ds_read_b128 v[176:179], v254 offset:3072
	v_mfma_f32_16x16x32_bf16 v[56:59], v[180:183], v[214:217], v[56:59]
	v_mfma_f32_16x16x32_bf16 v[48:51], v[188:191], v[214:217], v[48:51]
	ds_read_b128 v[214:217], v165
	v_mfma_f32_16x16x32_bf16 v[40:43], v[180:183], v[222:225], v[40:43]
	v_mfma_f32_16x16x32_bf16 v[32:35], v[188:191], v[222:225], v[32:35]
	ds_read_b128 v[222:225], v165 offset:2048
	v_mfma_f32_16x16x32_bf16 v[24:27], v[180:183], v[230:233], v[24:27]
	v_mfma_f32_16x16x32_bf16 v[16:19], v[188:191], v[230:233], v[16:19]
	ds_read_b128 v[230:233], v165 offset:4096
	v_mfma_f32_16x16x32_bf16 v[8:11], v[180:183], v[238:241], v[8:11]
	ds_read_b128 v[180:183], v254 offset:16384
	v_mfma_f32_16x16x32_bf16 v[0:3], v[188:191], v[238:241], v[0:3]
	ds_read_b128 v[188:191], v254 offset:18432
	ds_read_b128 v[238:241], v165 offset:6144
	v_mfma_f32_16x16x32_bf16 v[56:59], v[184:187], v[218:221], v[56:59]
	v_mfma_f32_16x16x32_bf16 v[48:51], v[210:213], v[218:221], v[48:51]
	ds_read_b128 v[218:221], v165 offset:1024
	v_mfma_f32_16x16x32_bf16 v[40:43], v[184:187], v[226:229], v[40:43]
	v_mfma_f32_16x16x32_bf16 v[32:35], v[210:213], v[226:229], v[32:35]
	ds_read_b128 v[226:229], v165 offset:3072
	v_mfma_f32_16x16x32_bf16 v[24:27], v[184:187], v[234:237], v[24:27]
	v_mfma_f32_16x16x32_bf16 v[16:19], v[210:213], v[234:237], v[16:19]
	ds_read_b128 v[234:237], v165 offset:5120
	v_mfma_f32_16x16x32_bf16 v[8:11], v[184:187], v[242:245], v[8:11]
	ds_read_b128 v[184:187], v254 offset:17408
	v_mfma_f32_16x16x32_bf16 v[0:3], v[210:213], v[242:245], v[0:3]
	ds_read_b128 v[210:213], v254 offset:19456
	ds_read_b128 v[242:245], v165 offset:7168
	s_setprio 0
	s_barrier
	s_add_i32 s53, s53, 2
	s_add_u32 s14, s14, 0x100
	s_addc_u32 s15, s15, 0
	s_add_u32 s51, s51, 0x100
	s_addc_u32 s52, s52, 0
	s_cmp_gt_u32 s53, 13
; #define PG8_STAGE(bufoff, gbase, voff) do { _Pragma("unroll") for (int _i = 0; _i < 2; ++_i) \
;         __builtin_amdgcn_global_load_lds((const unsigned*)((const char*)(gbase) + (voff)[_i]), (PG8_LAS unsigned*)(lds + (bufoff) + ldsw + _i * 8192), 16, 0, 0); } while (0)
; #define PG8_LDA(dst, b, h) do { _Pragma("unroll") for (int m = 0; m < 4; ++m) _Pragma("unroll") for (int k = 0; k < 2; ++k) dst[m][k] = *(const PG8_LAS bf16x8*)(lds + PG8_SA(b, h) + aoff + m * 2048 + k * 1024); } while (0)
; #define PG8_LDB(dst, b, h) do { _Pragma("unroll") for (int n = 0; n < 2; ++n) _Pragma("unroll") for (int k = 0; k < 2; ++k) dst[n][k] = *(const PG8_LAS bf16x8*)(lds + PG8_SB(b, h) + boff + n * 2048 + k * 1024); } while (0)
; #define PG8_MMA(ai, bj, At, Bt) do { __builtin_amdgcn_s_setprio(1); _Pragma("unroll") for (int m = 0; m < 4; ++m) _Pragma("unroll") for (int n = 0; n < 2; ++n) _Pragma("unroll") for (int k = 0; k < 2; ++k) \
;         acc[ai][bj][m][n] = __builtin_amdgcn_mfma_f32_16x16x32_bf16(Bt[n][k], At[m][k], acc[ai][bj][m][n], 0, 0, 0); __builtin_amdgcn_s_setprio(0); } while (0)
; #define PG8_WAIT_V(n) asm volatile("s_waitcnt vmcnt(" #n ")" ::: "memory")
; #define PG8_WAIT_L(n) asm volatile("s_waitcnt lgkmcnt(" #n ")" ::: "memory")
; template <class Epi, class Sched, bool ALIGN_EPI = false, bool SP2 = false>
; __device__ __forceinline__ void gemm_phase(PG8_LAS unsigned char* lds, const Gemm g, const Sched& S, const Epi& E) {
;     ...
;             const bool last = (t == nt - 2);
;             const char* a1 = cA + (size_t)(t + 1) * kstep;
;             const char* a2 = last ? nA : cA + (size_t)(t + 2) * kstep; const char* b2 = last ? nB : cB + (size_t)(t + 2) * kstep;
;             const char* a3 = a2 + kstep; const char* b3 = b2 + kstep;
;             if (last && has_next) S.a_ready(nxt);
;             if constexpr (SP2) {
;             PG8_LDB(B0, 0, 0); PG8_LDB(B1, 0, 1); PG8_SCHED; PG8_LDA(At, 0, 0); PG8_STAGE(PG8_SA(1, 1), a1 + hstep, voffA);
;             PG8_WAIT_V(8); PG8_WAIT_L(0); PG8_BAR; PG8_MMA(0, 0, At, B0); PG8_MMA(0, 1, At, B1); PG8_BAR; PG8_SCHED;
;             PG8_LDA(At, 0, 1); PG8_STAGE(PG8_SB(0, 0), b2, voffB); PG8_STAGE(PG8_SB(0, 1), b2 + hstep, voffB); PG8_STAGE(PG8_SA(0, 0), a2, voffA);
;             PG8_WAIT_V(8); PG8_WAIT_L(0); PG8_BAR; PG8_MMA(1, 0, At, B0); PG8_MMA(1, 1, At, B1); PG8_BAR; PG8_SCHED;
.Lup_loop_w1:
	s_add_u32 s16, s14, 0xfffc0080
	s_addc_u32 s17, s15, -1
	s_cmp_eq_u32 s53, 12
	s_cselect_b32 s19, s7, s17
	s_cselect_b32 s18, s49, s16
	s_cselect_b32 s17, s5, s52
	s_cselect_b32 s16, s50, s51
	s_mov_b32 m0, s43
	global_load_lds_dwordx4 v136, s[14:15]
	s_mov_b32 m0, s44
	s_nop 0
	global_load_lds_dwordx4 v138, s[14:15]
	s_waitcnt vmcnt(8)
	s_waitcnt lgkmcnt(0)
	s_barrier
	s_setprio 1
	v_mfma_f32_16x16x32_bf16 v[124:127], v[140:143], v[214:217], v[124:127]
	v_mfma_f32_16x16x32_bf16 v[116:119], v[172:175], v[214:217], v[116:119]
	v_mfma_f32_16x16x32_bf16 v[108:111], v[140:143], v[222:225], v[108:111]
	v_mfma_f32_16x16x32_bf16 v[100:103], v[172:175], v[222:225], v[100:103]
	v_mfma_f32_16x16x32_bf16 v[92:95], v[140:143], v[230:233], v[92:95]
	v_mfma_f32_16x16x32_bf16 v[84:87], v[172:175], v[230:233], v[84:87]
	v_mfma_f32_16x16x32_bf16 v[76:79], v[140:143], v[238:241], v[76:79]
	v_mfma_f32_16x16x32_bf16 v[68:71], v[172:175], v[238:241], v[68:71]
	v_mfma_f32_16x16x32_bf16 v[124:127], v[168:171], v[218:221], v[124:127]
	v_mfma_f32_16x16x32_bf16 v[116:119], v[176:179], v[218:221], v[116:119]
	v_mfma_f32_16x16x32_bf16 v[108:111], v[168:171], v[226:229], v[108:111]
	v_mfma_f32_16x16x32_bf16 v[100:103], v[176:179], v[226:229], v[100:103]
	v_mfma_f32_16x16x32_bf16 v[92:95], v[168:171], v[234:237], v[92:95]
	v_mfma_f32_16x16x32_bf16 v[84:87], v[176:179], v[234:237], v[84:87]
	v_mfma_f32_16x16x32_bf16 v[76:79], v[168:171], v[242:245], v[76:79]
	v_mfma_f32_16x16x32_bf16 v[68:71], v[176:179], v[242:245], v[68:71]
	v_mfma_f32_16x16x32_bf16 v[120:123], v[180:183], v[214:217], v[120:123]
	v_mfma_f32_16x16x32_bf16 v[112:115], v[188:191], v[214:217], v[112:115]
	ds_read_b128 v[214:217], v165 offset:16384
	v_mfma_f32_16x16x32_bf16 v[104:107], v[180:183], v[222:225], v[104:107]
	v_mfma_f32_16x16x32_bf16 v[96:99], v[188:191], v[222:225], v[96:99]
	ds_read_b128 v[222:225], v165 offset:18432
	v_mfma_f32_16x16x32_bf16 v[88:91], v[180:183], v[230:233], v[88:91]
	v_mfma_f32_16x16x32_bf16 v[80:83], v[188:191], v[230:233], v[80:83]
	ds_read_b128 v[230:233], v165 offset:20480
	v_mfma_f32_16x16x32_bf16 v[72:75], v[180:183], v[238:241], v[72:75]
	v_mfma_f32_16x16x32_bf16 v[64:67], v[188:191], v[238:241], v[64:67]
	ds_read_b128 v[238:241], v165 offset:22528
	v_mfma_f32_16x16x32_bf16 v[120:123], v[184:187], v[218:221], v[120:123]
	v_mfma_f32_16x16x32_bf16 v[112:115], v[210:213], v[218:221], v[112:115]
	ds_read_b128 v[218:221], v165 offset:17408
	v_mfma_f32_16x16x32_bf16 v[104:107], v[184:187], v[226:229], v[104:107]
	v_mfma_f32_16x16x32_bf16 v[96:99], v[210:213], v[226:229], v[96:99]
	ds_read_b128 v[226:229], v165 offset:19456
	v_mfma_f32_16x16x32_bf16 v[88:91], v[184:187], v[234:237], v[88:91]
	v_mfma_f32_16x16x32_bf16 v[80:83], v[210:213], v[234:237], v[80:83]
	ds_read_b128 v[234:237], v165 offset:21504
	v_mfma_f32_16x16x32_bf16 v[72:75], v[184:187], v[242:245], v[72:75]
	v_mfma_f32_16x16x32_bf16 v[64:67], v[210:213], v[242:245], v[64:67]
	ds_read_b128 v[242:245], v165 offset:23552
	s_setprio 0
	s_barrier
	s_mov_b32 m0, s27
	s_add_u32 s54, s16, 0x40000
	s_addc_u32 s55, s17, 0
	global_load_lds_dwordx4 v132, s[16:17]
	s_mov_b32 m0, s28
	s_nop 0
	global_load_lds_dwordx4 v128, s[16:17]
	s_mov_b32 m0, s29
	s_nop 0
	global_load_lds_dwordx4 v132, s[54:55]
	s_mov_b32 m0, s30
	s_nop 0
	global_load_lds_dwordx4 v128, s[54:55]
	s_mov_b32 m0, s22
	s_nop 0
	global_load_lds_dwordx4 v134, s[18:19]
	s_mov_b32 m0, s31
	s_nop 0
	global_load_lds_dwordx4 v130, s[18:19]
	s_waitcnt vmcnt(8)
	s_waitcnt lgkmcnt(0)
	s_barrier
	s_setprio 1
	v_mfma_f32_16x16x32_bf16 v[60:63], v[140:143], v[214:217], v[60:63]
	v_mfma_f32_16x16x32_bf16 v[52:55], v[172:175], v[214:217], v[52:55]
	v_mfma_f32_16x16x32_bf16 v[44:47], v[140:143], v[222:225], v[44:47]
	v_mfma_f32_16x16x32_bf16 v[36:39], v[172:175], v[222:225], v[36:39]
	v_mfma_f32_16x16x32_bf16 v[28:31], v[140:143], v[230:233], v[28:31]
	v_mfma_f32_16x16x32_bf16 v[20:23], v[172:175], v[230:233], v[20:23]
	v_mfma_f32_16x16x32_bf16 v[12:15], v[140:143], v[238:241], v[12:15]
	ds_read_b128 v[140:143], v254 offset:32768
	v_mfma_f32_16x16x32_bf16 v[4:7], v[172:175], v[238:241], v[4:7]
	ds_read_b128 v[172:175], v254 offset:34816
	v_mfma_f32_16x16x32_bf16 v[60:63], v[168:171], v[218:221], v[60:63]
	v_mfma_f32_16x16x32_bf16 v[52:55], v[176:179], v[218:221], v[52:55]
	v_mfma_f32_16x16x32_bf16 v[44:47], v[168:171], v[226:229], v[44:47]
	v_mfma_f32_16x16x32_bf16 v[36:39], v[176:179], v[226:229], v[36:39]
	v_mfma_f32_16x16x32_bf16 v[28:31], v[168:171], v[234:237], v[28:31]
	v_mfma_f32_16x16x32_bf16 v[20:23], v[176:179], v[234:237], v[20:23]
	v_mfma_f32_16x16x32_bf16 v[12:15], v[168:171], v[242:245], v[12:15]
	ds_read_b128 v[168:171], v254 offset:33792
	v_mfma_f32_16x16x32_bf16 v[4:7], v[176:179], v[242:245], v[4:7]
	ds_read_b128 v[176:179], v254 offset:35840
	v_mfma_f32_16x16x32_bf16 v[56:59], v[180:183], v[214:217], v[56:59]
	v_mfma_f32_16x16x32_bf16 v[48:51], v[188:191], v[214:217], v[48:51]
	ds_read_b128 v[214:217], v165 offset:32768
	v_mfma_f32_16x16x32_bf16 v[40:43], v[180:183], v[222:225], v[40:43]
	v_mfma_f32_16x16x32_bf16 v[32:35], v[188:191], v[222:225], v[32:35]
	ds_read_b128 v[222:225], v165 offset:34816
	v_mfma_f32_16x16x32_bf16 v[24:27], v[180:183], v[230:233], v[24:27]
	v_mfma_f32_16x16x32_bf16 v[16:19], v[188:191], v[230:233], v[16:19]
	ds_read_b128 v[230:233], v165 offset:36864
	v_mfma_f32_16x16x32_bf16 v[8:11], v[180:183], v[238:241], v[8:11]
	ds_read_b128 v[180:183], v254 offset:49152
	v_mfma_f32_16x16x32_bf16 v[0:3], v[188:191], v[238:241], v[0:3]
	ds_read_b128 v[188:191], v254 offset:51200
	ds_read_b128 v[238:241], v165 offset:38912
	v_mfma_f32_16x16x32_bf16 v[56:59], v[184:187], v[218:221], v[56:59]
	v_mfma_f32_16x16x32_bf16 v[48:51], v[210:213], v[218:221], v[48:51]
	ds_read_b128 v[218:221], v165 offset:33792
	v_mfma_f32_16x16x32_bf16 v[40:43], v[184:187], v[226:229], v[40:43]
	v_mfma_f32_16x16x32_bf16 v[32:35], v[210:213], v[226:229], v[32:35]
	ds_read_b128 v[226:229], v165 offset:35840
	v_mfma_f32_16x16x32_bf16 v[24:27], v[184:187], v[234:237], v[24:27]
	v_mfma_f32_16x16x32_bf16 v[16:19], v[210:213], v[234:237], v[16:19]
	ds_read_b128 v[234:237], v165 offset:37888
	v_mfma_f32_16x16x32_bf16 v[8:11], v[184:187], v[242:245], v[8:11]
	ds_read_b128 v[184:187], v254 offset:50176
	v_mfma_f32_16x16x32_bf16 v[0:3], v[210:213], v[242:245], v[0:3]
	ds_read_b128 v[210:213], v254 offset:52224
	ds_read_b128 v[242:245], v165 offset:39936
	s_setprio 0
	s_barrier
; #define PG8_STAGE(bufoff, gbase, voff) do { _Pragma("unroll") for (int _i = 0; _i < 2; ++_i) \
;         __builtin_amdgcn_global_load_lds((const unsigned*)((const char*)(gbase) + (voff)[_i]), (PG8_LAS unsigned*)(lds + (bufoff) + ldsw + _i * 8192), 16, 0, 0); } while (0)
; #define PG8_LDA(dst, b, h) do { _Pragma("unroll") for (int m = 0; m < 4; ++m) _Pragma("unroll") for (int k = 0; k < 2; ++k) dst[m][k] = *(const PG8_LAS bf16x8*)(lds + PG8_SA(b, h) + aoff + m * 2048 + k * 1024); } while (0)
; #define PG8_LDB(dst, b, h) do { _Pragma("unroll") for (int n = 0; n < 2; ++n) _Pragma("unroll") for (int k = 0; k < 2; ++k) dst[n][k] = *(const PG8_LAS bf16x8*)(lds + PG8_SB(b, h) + boff + n * 2048 + k * 1024); } while (0)
; #define PG8_MMA(ai, bj, At, Bt) do { __builtin_amdgcn_s_setprio(1); _Pragma("unroll") for (int m = 0; m < 4; ++m) _Pragma("unroll") for (int n = 0; n < 2; ++n) _Pragma("unroll") for (int k = 0; k < 2; ++k) \
;         acc[ai][bj][m][n] = __builtin_amdgcn_mfma_f32_16x16x32_bf16(Bt[n][k], At[m][k], acc[ai][bj][m][n], 0, 0, 0); __builtin_amdgcn_s_setprio(0); } while (0)
; #define PG8_WAIT_V(n) asm volatile("s_waitcnt vmcnt(" #n ")" ::: "memory")
; #define PG8_WAIT_L(n) asm volatile("s_waitcnt lgkmcnt(" #n ")" ::: "memory")
; #define PG8_BAR __builtin_amdgcn_s_barrier()
; #define PG8_SCHED __builtin_amdgcn_sched_barrier(0)
; template <class Epi, class Sched, bool ALIGN_EPI = false, bool SP2 = false>
; __device__ __forceinline__ void gemm_phase(PG8_LAS unsigned char* lds, const Gemm g, const Sched& S, const Epi& E) {
;     ...
;     for (;;) {
;         const bool has_next = S.next(ui + 1, nxt);
;         const char* nA = has_next ? (const char*)g.A + (size_t)nxt.pm * tstep : cA; const char* nB = has_next ? (const char*)g.Bt + (size_t)nxt.pn * tstep : cB;
;         for (int t = 0; t < nt; t += 2) {
;     ...
;             PG8_LDB(B0, 1, 0); PG8_LDB(B1, 1, 1); PG8_SCHED; PG8_LDA(At, 1, 0); PG8_STAGE(PG8_SA(0, 1), a2 + hstep, voffA);
;             PG8_WAIT_V(8); PG8_WAIT_L(0); PG8_BAR; PG8_MMA(0, 0, At, B0); PG8_MMA(0, 1, At, B1); PG8_BAR; PG8_SCHED;
;             PG8_LDA(At, 1, 1); PG8_STAGE(PG8_SB(1, 0), b3, voffB); PG8_STAGE(PG8_SB(1, 1), b3 + hstep, voffB); PG8_STAGE(PG8_SA(1, 0), a3, voffA);
;             PG8_WAIT_V(8); PG8_WAIT_L(0); PG8_BAR; PG8_MMA(1, 0, At, B0); PG8_MMA(1, 1, At, B1); PG8_BAR; PG8_SCHED;
	s_add_u32 s18, s18, 0x40000
	s_addc_u32 s19, s19, 0
	s_mov_b32 m0, s33
	global_load_lds_dwordx4 v134, s[18:19]
	s_mov_b32 m0, s34
	s_nop 0
	global_load_lds_dwordx4 v130, s[18:19]
	s_waitcnt vmcnt(8)
	s_waitcnt lgkmcnt(0)
	s_barrier
	s_setprio 1
	v_mfma_f32_16x16x32_bf16 v[124:127], v[140:143], v[214:217], v[124:127]
	v_mfma_f32_16x16x32_bf16 v[116:119], v[172:175], v[214:217], v[116:119]
	v_mfma_f32_16x16x32_bf16 v[108:111], v[140:143], v[222:225], v[108:111]
	v_mfma_f32_16x16x32_bf16 v[100:103], v[172:175], v[222:225], v[100:103]
	v_mfma_f32_16x16x32_bf16 v[92:95], v[140:143], v[230:233], v[92:95]
	v_mfma_f32_16x16x32_bf16 v[84:87], v[172:175], v[230:233], v[84:87]
	v_mfma_f32_16x16x32_bf16 v[76:79], v[140:143], v[238:241], v[76:79]
	v_mfma_f32_16x16x32_bf16 v[68:71], v[172:175], v[238:241], v[68:71]
	v_mfma_f32_16x16x32_bf16 v[124:127], v[168:171], v[218:221], v[124:127]
	v_mfma_f32_16x16x32_bf16 v[116:119], v[176:179], v[218:221], v[116:119]
	v_mfma_f32_16x16x32_bf16 v[108:111], v[168:171], v[226:229], v[108:111]
	v_mfma_f32_16x16x32_bf16 v[100:103], v[176:179], v[226:229], v[100:103]
	v_mfma_f32_16x16x32_bf16 v[92:95], v[168:171], v[234:237], v[92:95]
	v_mfma_f32_16x16x32_bf16 v[84:87], v[176:179], v[234:237], v[84:87]
	v_mfma_f32_16x16x32_bf16 v[76:79], v[168:171], v[242:245], v[76:79]
	v_mfma_f32_16x16x32_bf16 v[68:71], v[176:179], v[242:245], v[68:71]
	v_mfma_f32_16x16x32_bf16 v[120:123], v[180:183], v[214:217], v[120:123]
	v_mfma_f32_16x16x32_bf16 v[112:115], v[188:191], v[214:217], v[112:115]
	ds_read_b128 v[214:217], v165 offset:49152
	v_mfma_f32_16x16x32_bf16 v[104:107], v[180:183], v[222:225], v[104:107]
	v_mfma_f32_16x16x32_bf16 v[96:99], v[188:191], v[222:225], v[96:99]
	ds_read_b128 v[222:225], v165 offset:51200
	v_mfma_f32_16x16x32_bf16 v[88:91], v[180:183], v[230:233], v[88:91]
	v_mfma_f32_16x16x32_bf16 v[80:83], v[188:191], v[230:233], v[80:83]
	ds_read_b128 v[230:233], v165 offset:53248
	v_mfma_f32_16x16x32_bf16 v[72:75], v[180:183], v[238:241], v[72:75]
	v_mfma_f32_16x16x32_bf16 v[64:67], v[188:191], v[238:241], v[64:67]
	ds_read_b128 v[238:241], v165 offset:55296
	v_mfma_f32_16x16x32_bf16 v[120:123], v[184:187], v[218:221], v[120:123]
	v_mfma_f32_16x16x32_bf16 v[112:115], v[210:213], v[218:221], v[112:115]
	ds_read_b128 v[218:221], v165 offset:50176
	v_mfma_f32_16x16x32_bf16 v[104:107], v[184:187], v[226:229], v[104:107]
	v_mfma_f32_16x16x32_bf16 v[96:99], v[210:213], v[226:229], v[96:99]
	ds_read_b128 v[226:229], v165 offset:52224
	v_mfma_f32_16x16x32_bf16 v[88:91], v[184:187], v[234:237], v[88:91]
	v_mfma_f32_16x16x32_bf16 v[80:83], v[210:213], v[234:237], v[80:83]
	ds_read_b128 v[234:237], v165 offset:54272
	v_mfma_f32_16x16x32_bf16 v[72:75], v[184:187], v[242:245], v[72:75]
	v_mfma_f32_16x16x32_bf16 v[64:67], v[210:213], v[242:245], v[64:67]
	ds_read_b128 v[242:245], v165 offset:56320
	s_setprio 0
	s_barrier
	s_mov_b32 m0, s37
	s_add_u32 s16, s16, 0x40080
	s_addc_u32 s17, s17, 0
	s_add_u32 s98, s16, 0xfffc0000
	s_addc_u32 s99, s17, -1
	global_load_lds_dwordx4 v132, s[98:99]
	s_mov_b32 m0, s38
	s_nop 0
	global_load_lds_dwordx4 v128, s[98:99]
	s_mov_b32 m0, s41
	s_nop 0
	global_load_lds_dwordx4 v132, s[16:17]
	s_mov_b32 m0, s42
	s_nop 0
	global_load_lds_dwordx4 v128, s[16:17]
	s_mov_b32 m0, s39
	s_nop 0
	s_add_u32 s100, s18, 0xfffc0080
	s_addc_u32 s101, s19, -1
	global_load_lds_dwordx4 v134, s[100:101]
	s_mov_b32 m0, s40
	s_nop 0
	global_load_lds_dwordx4 v130, s[100:101]
	s_waitcnt vmcnt(8)
	s_waitcnt lgkmcnt(0)
	s_barrier
	s_setprio 1
	v_mfma_f32_16x16x32_bf16 v[60:63], v[140:143], v[214:217], v[60:63]
	v_mfma_f32_16x16x32_bf16 v[52:55], v[172:175], v[214:217], v[52:55]
	v_mfma_f32_16x16x32_bf16 v[44:47], v[140:143], v[222:225], v[44:47]
	v_mfma_f32_16x16x32_bf16 v[36:39], v[172:175], v[222:225], v[36:39]
	v_mfma_f32_16x16x32_bf16 v[28:31], v[140:143], v[230:233], v[28:31]
	v_mfma_f32_16x16x32_bf16 v[20:23], v[172:175], v[230:233], v[20:23]
	v_mfma_f32_16x16x32_bf16 v[12:15], v[140:143], v[238:241], v[12:15]
	ds_read_b128 v[140:143], v254
	v_mfma_f32_16x16x32_bf16 v[4:7], v[172:175], v[238:241], v[4:7]
	ds_read_b128 v[172:175], v254 offset:2048
	v_mfma_f32_16x16x32_bf16 v[60:63], v[168:171], v[218:221], v[60:63]
	v_mfma_f32_16x16x32_bf16 v[52:55], v[176:179], v[218:221], v[52:55]
	v_mfma_f32_16x16x32_bf16 v[44:47], v[168:171], v[226:229], v[44:47]
	v_mfma_f32_16x16x32_bf16 v[36:39], v[176:179], v[226:229], v[36:39]
	v_mfma_f32_16x16x32_bf16 v[28:31], v[168:171], v[234:237], v[28:31]
	v_mfma_f32_16x16x32_bf16 v[20:23], v[176:179], v[234:237], v[20:23]
	v_mfma_f32_16x16x32_bf16 v[12:15], v[168:171], v[242:245], v[12:15]
	ds_read_b128 v[168:171], v254 offset:1024
	v_mfma_f32_16x16x32_bf16 v[4:7], v[176:179], v[242:245], v[4:7]
	ds_read_b128 v[176:179], v254 offset:3072
	v_mfma_f32_16x16x32_bf16 v[56:59], v[180:183], v[214:217], v[56:59]
	v_mfma_f32_16x16x32_bf16 v[48:51], v[188:191], v[214:217], v[48:51]
	ds_read_b128 v[214:217], v165
	v_mfma_f32_16x16x32_bf16 v[40:43], v[180:183], v[222:225], v[40:43]
	v_mfma_f32_16x16x32_bf16 v[32:35], v[188:191], v[222:225], v[32:35]
	ds_read_b128 v[222:225], v165 offset:2048
	v_mfma_f32_16x16x32_bf16 v[24:27], v[180:183], v[230:233], v[24:27]
	v_mfma_f32_16x16x32_bf16 v[16:19], v[188:191], v[230:233], v[16:19]
	ds_read_b128 v[230:233], v165 offset:4096
	v_mfma_f32_16x16x32_bf16 v[8:11], v[180:183], v[238:241], v[8:11]
	ds_read_b128 v[180:183], v254 offset:16384
	v_mfma_f32_16x16x32_bf16 v[0:3], v[188:191], v[238:241], v[0:3]
	ds_read_b128 v[188:191], v254 offset:18432
	ds_read_b128 v[238:241], v165 offset:6144
	v_mfma_f32_16x16x32_bf16 v[56:59], v[184:187], v[218:221], v[56:59]
	v_mfma_f32_16x16x32_bf16 v[48:51], v[210:213], v[218:221], v[48:51]
	ds_read_b128 v[218:221], v165 offset:1024
	v_mfma_f32_16x16x32_bf16 v[40:43], v[184:187], v[226:229], v[40:43]
	v_mfma_f32_16x16x32_bf16 v[32:35], v[210:213], v[226:229], v[32:35]
	ds_read_b128 v[226:229], v165 offset:3072
	v_mfma_f32_16x16x32_bf16 v[24:27], v[184:187], v[234:237], v[24:27]
	v_mfma_f32_16x16x32_bf16 v[16:19], v[210:213], v[234:237], v[16:19]
	ds_read_b128 v[234:237], v165 offset:5120
	v_mfma_f32_16x16x32_bf16 v[8:11], v[184:187], v[242:245], v[8:11]
	ds_read_b128 v[184:187], v254 offset:17408
	v_mfma_f32_16x16x32_bf16 v[0:3], v[210:213], v[242:245], v[0:3]
	ds_read_b128 v[210:213], v254 offset:19456
	ds_read_b128 v[242:245], v165 offset:7168
	s_setprio 0
	s_barrier
	s_add_i32 s53, s53, 2
	s_add_u32 s14, s14, 0x100
	s_addc_u32 s15, s15, 0
	s_add_u32 s51, s51, 0x100
	s_addc_u32 s52, s52, 0
	s_cmp_gt_u32 s53, 13
	s_cbranch_scc0 .Lup_loop_w1
	s_waitcnt lgkmcnt(0)
	s_branch .LBB0_449

; template <class Epi, class Sched, bool ALIGN_EPI = false, bool SP2 = false>
; __device__ __forceinline__ void gemm_phase(PG8_LAS unsigned char* lds, const Gemm g, const Sched& S, const Epi& E) {
;     ...
;         const bool has_next = S.next(ui + 1, nxt);
;         const char* nA = has_next ? (const char*)g.A + (size_t)nxt.pm * tstep : cA; const char* nB = has_next ? (const char*)g.Bt + (size_t)nxt.pn * tstep : cB;
;         for (int t = 0; t < nt; t += 2) {
;             const bool last = (t == nt - 2);
;             const char* a1 = cA + (size_t)(t + 1) * kstep;
;             const char* a2 = last ? nA : cA + (size_t)(t + 2) * kstep; const char* b2 = last ? nB : cB + (size_t)(t + 2) * kstep;
.LBB0_445:
	s_ashr_i32 s7, s6, 31
	s_lshl_b64 s[10:11], s[6:7], 19
	s_add_u32 s10, s23, s10
	s_addc_u32 s11, s24, s11
	s_and_b64 s[12:13], s[8:9], exec
	s_cselect_b32 s7, s11, s15
	s_cselect_b32 s49, s10, s14
	s_ashr_i32 s5, s4, 31
	s_lshl_b64 s[12:13], s[4:5], 19
	s_add_u32 s12, s25, s12
	s_addc_u32 s13, s26, s13
	s_and_b64 s[18:19], s[8:9], exec
	s_cselect_b32 s5, s13, s17
	s_cselect_b32 s50, s12, s16
	s_add_u32 s14, s14, 0x40080
	s_addc_u32 s15, s15, 0
	s_add_u32 s51, s16, 0x100
	v_mov_b32_e32 v0, 0
	s_addc_u32 s52, s17, 0
	s_mov_b32 s53, -2
	v_add_u32_e32 v254, 0x10000, v166
	s_cmp_lg_u64 s[2:3], 0
	s_cbranch_scc0 .Lup_peel_w1
